# v10 + constant group-size (WGM=4) reciprocal in the unit scheduler as well (17 more sites)
# baseline (speedup 1.0000x reference)
;     __device__ __forceinline__ bool next(int i, Unit& u) const {
;         int nM = this->nM, nN = this->nN, Z2 = this->Z2; asm volatile("" : "+s"(nM), "+s"(nN), "+s"(Z2));
;         const long L = (long)i * G + c; if (L >= nwg) return false;
;         int wgid = (int)L; { const int q = nwg / NXCD, r = nwg % NXCD, xcd = wgid % NXCD, off = wgid / NXCD; wgid = (xcd < r ? xcd * (q + 1) : r * (q + 1) + (xcd - r) * q) + off; }
;         if (rev) wgid = nwg - 1 - wgid;
;         const int per = nM * nN, z = wgid / per, rem = wgid - z * per;
;         const int nig = WGM * nN, gid = rem / nig, fm = gid * WGM, gsz = (nM - fm) < WGM ? (nM - fm) : WGM, ri = rem - gid * nig;
;         u.pm = fm + (ri % gsz); u.pn = ri / gsz; u.z1 = z / Z2; u.z2 = z - u.z1 * Z2; return true;
; template <class Epi>
; __device__ __forceinline__ void gemm_phase(PG8_LAS unsigned char* lds, PG8_LAS unsigned char* xl, const Gemm g, const Sched& S, const Epi& E, const int wid) {
;     ...
;         const bool has_next = S.next(ui + 1, nxt);
.LBB0_217:
	s_mov_b32 s8, 20
	s_mov_b32 s10, 1
	s_mov_b32 s9, 16
	s_add_i32 s89, s89, 1
	s_mul_i32 s10, s89, s88
	s_mul_hi_u32 s11, s89, s0
	s_add_i32 s11, s11, s10
	s_mul_i32 s10, s89, s0
	s_add_u32 s10, s10, s1
	s_addc_u32 s11, s11, s67
	v_mov_b64_e32 v[0:1], 0x140
	v_cmp_lt_i64_e64 s[40:41], s[10:11], v[0:1]
	v_mov_b64_e32 v[0:1], 0x13f
	v_cmp_gt_i64_e32 vcc, s[10:11], v[0:1]
	s_cbranch_vccnz .LBB0_219
	s_ashr_i32 s11, s10, 31
	s_lshr_b32 s11, s11, 29
	s_add_i32 s11, s10, s11
	s_ashr_i32 s12, s11, 3
	s_and_b32 s11, s11, -8
	s_sub_i32 s10, s10, s11
	s_cmp_lt_i32 s10, 0
	s_mul_i32 s13, s8, s9
	s_cselect_b32 s11, 41, 40
	s_abs_i32 s13, s13
	s_mul_i32 s10, s10, s11
	s_sub_i32 s11, 0, s13
	s_add_i32 s10, s10, s12
	s_ashr_i32 s12, s10, 31
	s_abs_i32 s10, s10
	s_mov_b32 s20, 0xcccccc
	s_mul_i32 s11, s11, s20
	s_mul_hi_u32 s11, s20, s11
	s_add_i32 s20, s20, s11
	s_mul_hi_u32 s11, s10, s20
	s_mul_i32 s11, s11, s13
	s_sub_i32 s10, s10, s11
	s_sub_i32 s11, s10, s13
	s_cmp_ge_u32 s10, s13
	s_cselect_b32 s10, s11, s10
	s_sub_i32 s11, s10, s13
	s_cmp_ge_u32 s10, s13
	s_cselect_b32 s10, s11, s10
	s_lshl_b32 s9, s9, 2
	s_abs_i32 s11, s9
	s_xor_b32 s10, s10, s12
	s_sub_i32 s10, s10, s12
	s_sub_i32 s12, 0, s11
	s_abs_i32 s20, s10
	s_xor_b32 s13, s10, s9
	s_ashr_i32 s13, s13, 31
	s_mov_b32 s21, 0x4000000
	s_mul_i32 s12, s12, s21
	s_mul_hi_u32 s12, s21, s12
	s_add_i32 s21, s21, s12
	s_mul_hi_u32 s12, s20, s21
	s_mul_i32 s21, s12, s11
	s_sub_i32 s20, s20, s21
	s_add_i32 s30, s12, 1
	s_sub_i32 s21, s20, s11
	s_cmp_ge_u32 s20, s11
	s_cselect_b32 s12, s30, s12
	s_cselect_b32 s20, s21, s20
	s_add_i32 s21, s12, 1
	s_cmp_ge_u32 s20, s11
	s_cselect_b32 s11, s21, s12
	s_xor_b32 s11, s11, s13
	s_sub_i32 s11, s11, s13
	s_lshl_b32 s13, s11, 2
	s_sub_i32 s8, s8, s13
	s_min_i32 s8, s8, 4
	s_abs_i32 s12, s8
	s_sub_i32 s20, 0, s12
	s_mul_i32 s11, s11, s9
	s_sub_i32 s9, s10, s11
	s_abs_i32 s10, s9
	s_xor_b32 s11, s9, s8
	s_ashr_i32 s11, s11, 31
	s_mov_b32 s21, 0x40000000
	s_mul_i32 s20, s20, s21
	s_mul_hi_u32 s20, s21, s20
	s_add_i32 s21, s21, s20
	s_mul_hi_u32 s20, s10, s21
	s_mul_i32 s21, s20, s12
	s_sub_i32 s10, s10, s21
	s_add_i32 s30, s20, 1
	s_sub_i32 s21, s10, s12
	s_cmp_ge_u32 s10, s12
	s_cselect_b32 s20, s30, s20
	s_cselect_b32 s10, s21, s10
	s_add_i32 s21, s20, 1
	s_cmp_ge_u32 s10, s12
	s_cselect_b32 s10, s21, s20
	s_xor_b32 s10, s10, s11
	s_sub_i32 s12, s10, s11
	s_mul_i32 s8, s12, s8
	s_sub_i32 s8, s9, s8
	s_add_i32 s20, s13, s8

;     __device__ __forceinline__ bool next(int i, Unit& u) const {
;         int nM = this->nM, nN = this->nN, Z2 = this->Z2; asm volatile("" : "+s"(nM), "+s"(nN), "+s"(Z2));
;         const long L = (long)i * G + c; if (L >= nwg) return false;
;         int wgid = (int)L; { const int q = nwg / NXCD, r = nwg % NXCD, xcd = wgid % NXCD, off = wgid / NXCD; wgid = (xcd < r ? xcd * (q + 1) : r * (q + 1) + (xcd - r) * q) + off; }
;         if (rev) wgid = nwg - 1 - wgid;
;         const int per = nM * nN, z = wgid / per, rem = wgid - z * per;
;         const int nig = WGM * nN, gid = rem / nig, fm = gid * WGM, gsz = (nM - fm) < WGM ? (nM - fm) : WGM, ri = rem - gid * nig;
;         u.pm = fm + (ri % gsz); u.pn = ri / gsz; u.z1 = z / Z2; u.z2 = z - u.z1 * Z2; return true;
; template <class Epi>
; __device__ __forceinline__ void gemm_phase(PG8_LAS unsigned char* lds, PG8_LAS unsigned char* xl, const Gemm g, const Sched& S, const Epi& E, const int wid) {
;     ...
;     if (!S.next(0, cur)) return;
.LBB0_227:
	v_readlane_b32 s4, v254, 20
	v_readlane_b32 s5, v254, 21
	s_mov_b32 s9, 1
	s_movk_i32 s1, 0xa0
	v_cndmask_b32_e64 v0, 0, 1, s[4:5]
	s_mov_b32 s8, 28
	v_cmp_ne_u32_e64 s[40:41], 1, v0
	s_andn2_b64 vcc, exec, s[4:5]
	v_mbcnt_lo_u32_b32 v8, -1, 0
	v_mbcnt_hi_u32_b32 v8, -1, v8
	s_cbranch_vccnz .LBB0_229
	s_mul_i32 s9, s1, s8
	s_abs_i32 s9, s9
	s_sub_i32 s10, 0, s9
	v_readlane_b32 s4, v254, 49
	s_nop 0
	s_mov_b32 s11, 0xea0ea
	s_mul_i32 s10, s10, s11
	s_mul_hi_u32 s10, s11, s10
	s_add_i32 s11, s11, s10
	s_mul_hi_u32 s10, s4, s11
	s_mul_i32 s10, s10, s9
	s_sub_i32 s10, s4, s10
	s_sub_i32 s11, s10, s9
	s_cmp_ge_u32 s10, s9
	s_cselect_b32 s10, s11, s10
	s_sub_i32 s11, s10, s9
	s_cmp_ge_u32 s10, s9
	s_cselect_b32 s9, s11, s10
	s_lshl_b32 s8, s8, 2
	s_abs_i32 s10, s8
	v_readlane_b32 s4, v254, 48
	s_sub_i32 s11, 0, s10
	s_xor_b32 s9, s9, s4
	s_sub_i32 s9, s9, s4
	s_abs_i32 s13, s9
	s_xor_b32 s12, s9, s8
	s_ashr_i32 s12, s12, 31
	s_mov_b32 s20, 0x2492492
	s_mul_i32 s11, s11, s20
	s_mul_hi_u32 s11, s20, s11
	s_add_i32 s20, s20, s11
	s_mul_hi_u32 s11, s13, s20
	s_mul_i32 s20, s11, s10
	s_sub_i32 s13, s13, s20
	s_add_i32 s21, s11, 1
	s_sub_i32 s20, s13, s10
	s_cmp_ge_u32 s13, s10
	s_cselect_b32 s11, s21, s11
	s_cselect_b32 s13, s20, s13
	s_add_i32 s20, s11, 1
	s_cmp_ge_u32 s13, s10
	s_cselect_b32 s10, s20, s11
	s_xor_b32 s10, s10, s12
	s_sub_i32 s10, s10, s12
	s_lshl_b32 s11, s10, 2
	s_sub_i32 s1, s1, s11
	s_min_i32 s1, s1, 4
	s_abs_i32 s12, s1
	s_sub_i32 s13, 0, s12
	s_mul_i32 s10, s10, s8
	s_sub_i32 s8, s9, s10
	s_abs_i32 s9, s8
	s_xor_b32 s10, s8, s1
	s_ashr_i32 s10, s10, 31
	s_mov_b32 s20, 0x40000000
	s_mul_i32 s13, s13, s20
	s_mul_hi_u32 s13, s20, s13
	s_add_i32 s20, s20, s13
	s_mul_hi_u32 s13, s9, s20
	s_mul_i32 s20, s13, s12
	s_sub_i32 s9, s9, s20
	s_add_i32 s21, s13, 1
	s_sub_i32 s20, s9, s12
	s_cmp_ge_u32 s9, s12
	s_cselect_b32 s13, s21, s13
	s_cselect_b32 s9, s20, s9
	s_add_i32 s20, s13, 1
	s_cmp_ge_u32 s9, s12
	s_cselect_b32 s9, s20, s13
	s_xor_b32 s9, s9, s10
	s_sub_i32 s12, s9, s10
	s_mul_i32 s1, s12, s1
	s_sub_i32 s1, s8, s1
	s_add_i32 s48, s11, s1

;     __device__ __forceinline__ bool next(int i, Unit& u) const {
;         int nM = this->nM, nN = this->nN, Z2 = this->Z2; asm volatile("" : "+s"(nM), "+s"(nN), "+s"(Z2));
;         const long L = (long)i * G + c; if (L >= nwg) return false;
;         int wgid = (int)L; { const int q = nwg / NXCD, r = nwg % NXCD, xcd = wgid % NXCD, off = wgid / NXCD; wgid = (xcd < r ? xcd * (q + 1) : r * (q + 1) + (xcd - r) * q) + off; }
;         if (rev) wgid = nwg - 1 - wgid;
;         const int per = nM * nN, z = wgid / per, rem = wgid - z * per;
;         const int nig = WGM * nN, gid = rem / nig, fm = gid * WGM, gsz = (nM - fm) < WGM ? (nM - fm) : WGM, ri = rem - gid * nig;
;         u.pm = fm + (ri % gsz); u.pn = ri / gsz; u.z1 = z / Z2; u.z2 = z - u.z1 * Z2; return true;
; template <class Epi>
; __device__ __forceinline__ void gemm_phase(PG8_LAS unsigned char* lds, PG8_LAS unsigned char* xl, const Gemm g, const Sched& S, const Epi& E, const int wid) {
;     ...
;         const bool has_next = S.next(ui + 1, nxt);
.LBB0_235:
	s_mov_b32 s10, 1
	s_movk_i32 s8, 0xa0
	s_mov_b32 s9, 28
	s_add_i32 s96, s96, 1
	s_mul_i32 s10, s96, s95
	s_mul_hi_u32 s11, s96, s0
	s_add_i32 s11, s11, s10
	s_mul_i32 s10, s96, s0
	s_add_u32 s10, s10, s2
	s_addc_u32 s11, s11, s33
	v_mov_b64_e32 v[0:1], 0x1180
	v_cmp_lt_i64_e64 s[40:41], s[10:11], v[0:1]
	v_mov_b64_e32 v[0:1], 0x117f
	v_cmp_gt_i64_e64 s[42:43], s[10:11], v[0:1]
	s_and_b64 vcc, exec, s[42:43]
	s_cbranch_vccnz .LBB0_237
	s_ashr_i32 s11, s10, 31
	s_lshr_b32 s11, s11, 29
	s_add_i32 s11, s10, s11
	s_and_b32 s13, s11, -8
	s_sub_i32 s10, s10, s13
	s_ashr_i32 s11, s11, 3
	s_cmp_lt_i32 s10, 0
	s_mul_i32 s36, s8, s9
	s_cselect_b32 s13, s4, 0xfffffdd0
	s_abs_i32 s36, s36
	s_mul_i32 s10, s10, s13
	s_sub_i32 s13, 0, s36
	s_sub_i32 s10, s10, s11
	s_addk_i32 s10, 0x117f
	s_ashr_i32 s11, s10, 31
	s_abs_i32 s10, s10
	s_mov_b32 s37, 0xea0ea
	s_mul_i32 s13, s13, s37
	s_mul_hi_u32 s13, s37, s13
	s_add_i32 s37, s37, s13
	s_mul_hi_u32 s13, s10, s37
	s_mul_i32 s13, s13, s36
	s_sub_i32 s10, s10, s13
	s_sub_i32 s13, s10, s36
	s_cmp_ge_u32 s10, s36
	s_cselect_b32 s10, s13, s10
	s_sub_i32 s13, s10, s36
	s_cmp_ge_u32 s10, s36
	s_cselect_b32 s10, s13, s10
	s_lshl_b32 s9, s9, 2
	s_abs_i32 s13, s9
	s_xor_b32 s10, s10, s11
	s_sub_i32 s10, s10, s11
	s_sub_i32 s11, 0, s13
	s_abs_i32 s37, s10
	s_xor_b32 s36, s10, s9
	s_ashr_i32 s36, s36, 31
	s_mov_b32 s44, 0x2492492
	s_mul_i32 s11, s11, s44
	s_mul_hi_u32 s11, s44, s11
	s_add_i32 s44, s44, s11
	s_mul_hi_u32 s11, s37, s44
	s_mul_i32 s44, s11, s13
	s_sub_i32 s37, s37, s44
	s_add_i32 s45, s11, 1
	s_sub_i32 s44, s37, s13
	s_cmp_ge_u32 s37, s13
	s_cselect_b32 s11, s45, s11
	s_cselect_b32 s37, s44, s37
	s_add_i32 s44, s11, 1
	s_cmp_ge_u32 s37, s13
	s_cselect_b32 s11, s44, s11
	s_xor_b32 s11, s11, s36
	s_sub_i32 s11, s11, s36
	s_lshl_b32 s13, s11, 2
	s_sub_i32 s8, s8, s13
	s_min_i32 s8, s8, 4
	s_abs_i32 s36, s8
	s_sub_i32 s37, 0, s36
	s_mul_i32 s11, s11, s9
	s_sub_i32 s9, s10, s11
	s_abs_i32 s10, s9
	s_xor_b32 s11, s9, s8
	s_ashr_i32 s11, s11, 31
	s_mov_b32 s44, 0x40000000
	s_mul_i32 s37, s37, s44
	s_mul_hi_u32 s37, s44, s37
	s_add_i32 s44, s44, s37
	s_mul_hi_u32 s37, s10, s44
	s_mul_i32 s44, s37, s36
	s_sub_i32 s10, s10, s44
	s_add_i32 s45, s37, 1
	s_sub_i32 s44, s10, s36
	s_cmp_ge_u32 s10, s36
	s_cselect_b32 s37, s45, s37
	s_cselect_b32 s10, s44, s10
	s_add_i32 s44, s37, 1
	s_cmp_ge_u32 s10, s36
	s_cselect_b32 s10, s44, s37
	s_xor_b32 s10, s10, s11
	s_sub_i32 s56, s10, s11
	s_mul_i32 s8, s56, s8
	s_sub_i32 s8, s9, s8
	s_add_i32 s58, s13, s8

;     __device__ __forceinline__ bool next(int i, Unit& u) const {
;         int nM = this->nM, nN = this->nN, Z2 = this->Z2; asm volatile("" : "+s"(nM), "+s"(nN), "+s"(Z2));
;         const long L = (long)i * G + c; if (L >= nwg) return false;
;         int wgid = (int)L; { const int q = nwg / NXCD, r = nwg % NXCD, xcd = wgid % NXCD, off = wgid / NXCD; wgid = (xcd < r ? xcd * (q + 1) : r * (q + 1) + (xcd - r) * q) + off; }
;         if (rev) wgid = nwg - 1 - wgid;
;         const int per = nM * nN, z = wgid / per, rem = wgid - z * per;
;         const int nig = WGM * nN, gid = rem / nig, fm = gid * WGM, gsz = (nM - fm) < WGM ? (nM - fm) : WGM, ri = rem - gid * nig;
;         u.pm = fm + (ri % gsz); u.pn = ri / gsz; u.z1 = z / Z2; u.z2 = z - u.z1 * Z2; return true;
; template <class Epi>
; __device__ __forceinline__ void gemm_phase(PG8_LAS unsigned char* lds, PG8_LAS unsigned char* xl, const Gemm g, const Sched& S, const Epi& E, const int wid) {
;     ...
;         const bool has_next = S.next(ui + 1, nxt);
.LBB0_421:
	s_add_i32 s93, s93, 1
	s_mul_i32 s10, s93, s92
	s_mul_hi_u32 s11, s93, s87
	s_add_i32 s11, s11, s10
	s_mul_i32 s10, s93, s87
	s_add_u32 s10, s10, s0
	s_addc_u32 s11, s11, s68
	v_cmp_gt_i64_e32 vcc, s[10:11], v[198:199]
	s_mov_b32 s9, 8
	s_mov_b32 s21, 1
	s_mov_b32 s8, 4
	v_cmp_lt_i64_e64 s[46:47], s[10:11], v[196:197]
	s_cbranch_vccnz .LBB0_423
	s_ashr_i32 s11, s10, 31
	s_lshr_b32 s11, s11, 29
	s_add_i32 s11, s10, s11
	s_ashr_i32 s30, s11, 3
	s_and_b32 s11, s11, -8
	s_sub_i32 s10, s10, s11
	s_cmp_lt_i32 s10, 0
	s_movk_i32 s4, 0x51
	s_mul_i32 s31, s9, s21
	s_cselect_b32 s11, s4, 0x50
	s_abs_i32 s36, s31
	s_mul_i32 s10, s10, s11
	s_sub_i32 s11, 0, s36
	s_add_i32 s10, s10, s30
	s_abs_i32 s37, s10
	s_xor_b32 s30, s10, s31
	s_ashr_i32 s30, s30, 31
	s_mov_b32 s40, 0x20000000
	s_mul_i32 s11, s11, s40
	s_mul_hi_u32 s11, s40, s11
	s_add_i32 s40, s40, s11
	s_mul_hi_u32 s11, s37, s40
	s_mul_i32 s40, s11, s36
	s_sub_i32 s37, s37, s40
	s_add_i32 s40, s11, 1
	s_sub_i32 s41, s37, s36
	s_cmp_ge_u32 s37, s36
	s_cselect_b32 s11, s40, s11
	s_cselect_b32 s37, s41, s37
	s_add_i32 s40, s11, 1
	s_cmp_ge_u32 s37, s36
	s_cselect_b32 s11, s40, s11
	s_lshl_b32 s21, s21, 2
	s_abs_i32 s36, s21
	s_xor_b32 s11, s11, s30
	s_sub_i32 s11, s11, s30
	s_sub_i32 s37, 0, s36
	s_mul_i32 s30, s11, s31
	s_sub_i32 s10, s10, s30
	s_abs_i32 s31, s10
	s_xor_b32 s30, s10, s21
	s_ashr_i32 s30, s30, 31
	s_mov_b32 s40, 0x40000000
	s_mul_i32 s37, s37, s40
	s_mul_hi_u32 s37, s40, s37
	s_add_i32 s40, s40, s37
	s_mul_hi_u32 s37, s31, s40
	s_mul_i32 s40, s37, s36
	s_sub_i32 s31, s31, s40
	s_add_i32 s40, s37, 1
	s_sub_i32 s41, s31, s36
	s_cmp_ge_u32 s31, s36
	s_cselect_b32 s37, s40, s37
	s_cselect_b32 s31, s41, s31
	s_add_i32 s40, s37, 1
	s_cmp_ge_u32 s31, s36
	s_cselect_b32 s31, s40, s37
	s_xor_b32 s31, s31, s30
	s_sub_i32 s30, s31, s30
	s_lshl_b32 s31, s30, 2
	s_sub_i32 s9, s9, s31
	s_min_i32 s9, s9, 4
	s_abs_i32 s36, s9
	s_sub_i32 s37, 0, s36
	s_mul_i32 s30, s30, s21
	s_sub_i32 s10, s10, s30
	s_abs_i32 s30, s10
	s_xor_b32 s21, s10, s9
	s_ashr_i32 s21, s21, 31
	s_mov_b32 s40, 0x40000000
	s_mul_i32 s37, s37, s40
	s_mul_hi_u32 s37, s40, s37
	s_add_i32 s40, s40, s37
	s_mul_hi_u32 s37, s30, s40
	s_mul_i32 s40, s37, s36
	s_sub_i32 s30, s30, s40
	s_add_i32 s40, s37, 1
	s_sub_i32 s41, s30, s36
	s_cmp_ge_u32 s30, s36
	s_cselect_b32 s37, s40, s37
	s_cselect_b32 s30, s41, s30
	s_add_i32 s40, s37, 1
	s_cmp_ge_u32 s30, s36
	s_cselect_b32 s30, s40, s37
	s_abs_i32 s37, s8
	s_xor_b32 s30, s30, s21
	s_sub_i32 s30, s30, s21
	s_mul_i32 s9, s30, s9
	s_sub_i32 s9, s10, s9
	s_add_i32 s36, s31, s9
	s_sub_i32 s21, 0, s37
	s_abs_i32 s10, s11
	s_xor_b32 s9, s11, s8
	s_ashr_i32 s9, s9, 31
	s_mov_b32 s31, 0x40000000
	s_mul_i32 s21, s21, s31
	s_mul_hi_u32 s21, s31, s21
	s_add_i32 s31, s31, s21
	s_mul_hi_u32 s21, s10, s31
	s_mul_i32 s31, s21, s37
	s_sub_i32 s10, s10, s31
	s_add_i32 s31, s21, 1
	s_sub_i32 s40, s10, s37
	s_cmp_ge_u32 s10, s37
	s_cselect_b32 s21, s31, s21
	s_cselect_b32 s10, s40, s10
	s_add_i32 s31, s21, 1
	s_cmp_ge_u32 s10, s37
	s_cselect_b32 s10, s31, s21
	s_xor_b32 s10, s10, s9
	s_sub_i32 s50, s10, s9
	s_mul_i32 s8, s50, s8
	s_sub_i32 s52, s11, s8

;     __device__ __forceinline__ bool next(int i, Unit& u) const {
;         int nM = this->nM, nN = this->nN, Z2 = this->Z2; asm volatile("" : "+s"(nM), "+s"(nN), "+s"(Z2));
;         const long L = (long)i * G + c; if (L >= nwg) return false;
;         int wgid = (int)L; { const int q = nwg / NXCD, r = nwg % NXCD, xcd = wgid % NXCD, off = wgid / NXCD; wgid = (xcd < r ? xcd * (q + 1) : r * (q + 1) + (xcd - r) * q) + off; }
;         if (rev) wgid = nwg - 1 - wgid;
;         const int per = nM * nN, z = wgid / per, rem = wgid - z * per;
;         const int nig = WGM * nN, gid = rem / nig, fm = gid * WGM, gsz = (nM - fm) < WGM ? (nM - fm) : WGM, ri = rem - gid * nig;
;         u.pm = fm + (ri % gsz); u.pn = ri / gsz; u.z1 = z / Z2; u.z2 = z - u.z1 * Z2; return true;
; template <class Epi>
; __device__ __forceinline__ void gemm_phase(PG8_LAS unsigned char* lds, PG8_LAS unsigned char* xl, const Gemm g, const Sched& S, const Epi& E, const int wid) {
;     ...
;     if (!S.next(0, cur)) return;
.LBB0_516:
	v_readlane_b32 s4, v254, 36
	v_readlane_b32 s5, v254, 37
	s_mov_b32 s10, 1
	s_movk_i32 s8, 0xa0
	v_cndmask_b32_e64 v0, 0, 1, s[4:5]
	s_mov_b32 s9, 16
	v_cmp_ne_u32_e64 s[46:47], 1, v0
	s_andn2_b64 vcc, exec, s[4:5]
	v_mbcnt_lo_u32_b32 v8, -1, 0
	v_mbcnt_hi_u32_b32 v8, -1, v8
	s_cbranch_vccnz .LBB0_518
	s_mul_i32 s10, s8, s9
	s_abs_i32 s10, s10
	s_sub_i32 s11, 0, s10
	v_readlane_b32 s4, v254, 51
	s_nop 0
	s_mov_b32 s12, 0x199999
	s_mul_i32 s11, s11, s12
	s_mul_hi_u32 s11, s12, s11
	s_add_i32 s12, s12, s11
	s_mul_hi_u32 s11, s4, s12
	s_mul_i32 s11, s11, s10
	s_sub_i32 s11, s4, s11
	s_sub_i32 s12, s11, s10
	s_cmp_ge_u32 s11, s10
	s_cselect_b32 s11, s12, s11
	s_sub_i32 s12, s11, s10
	s_cmp_ge_u32 s11, s10
	s_cselect_b32 s10, s12, s11
	s_lshl_b32 s9, s9, 2
	s_abs_i32 s11, s9
	v_readlane_b32 s4, v254, 50
	s_sub_i32 s12, 0, s11
	s_xor_b32 s10, s10, s4
	s_sub_i32 s10, s10, s4
	s_abs_i32 s20, s10
	s_xor_b32 s13, s10, s9
	s_ashr_i32 s13, s13, 31
	s_mov_b32 s21, 0x4000000
	s_mul_i32 s12, s12, s21
	s_mul_hi_u32 s12, s21, s12
	s_add_i32 s21, s21, s12
	s_mul_hi_u32 s12, s20, s21
	s_mul_i32 s21, s12, s11
	s_sub_i32 s20, s20, s21
	s_add_i32 s30, s12, 1
	s_sub_i32 s21, s20, s11
	s_cmp_ge_u32 s20, s11
	s_cselect_b32 s12, s30, s12
	s_cselect_b32 s20, s21, s20
	s_add_i32 s21, s12, 1
	s_cmp_ge_u32 s20, s11
	s_cselect_b32 s11, s21, s12
	s_xor_b32 s11, s11, s13
	s_sub_i32 s11, s11, s13
	s_lshl_b32 s12, s11, 2
	s_sub_i32 s8, s8, s12
	s_min_i32 s8, s8, 4
	s_abs_i32 s13, s8
	s_sub_i32 s20, 0, s13
	s_mul_i32 s11, s11, s9
	s_sub_i32 s9, s10, s11
	s_abs_i32 s10, s9
	s_xor_b32 s11, s9, s8
	s_ashr_i32 s11, s11, 31
	s_mov_b32 s21, 0x40000000
	s_mul_i32 s20, s20, s21
	s_mul_hi_u32 s20, s21, s20
	s_add_i32 s21, s21, s20
	s_mul_hi_u32 s20, s10, s21
	s_mul_i32 s21, s20, s13
	s_sub_i32 s10, s10, s21
	s_add_i32 s30, s20, 1
	s_sub_i32 s21, s10, s13
	s_cmp_ge_u32 s10, s13
	s_cselect_b32 s20, s30, s20
	s_cselect_b32 s10, s21, s10
	s_add_i32 s21, s20, 1
	s_cmp_ge_u32 s10, s13
	s_cselect_b32 s10, s21, s20
	s_xor_b32 s10, s10, s11
	s_sub_i32 s44, s10, s11
	s_mul_i32 s8, s44, s8
	s_sub_i32 s8, s9, s8
	s_add_i32 s40, s12, s8

;     __device__ __forceinline__ bool next(int i, Unit& u) const {
;         int nM = this->nM, nN = this->nN, Z2 = this->Z2; asm volatile("" : "+s"(nM), "+s"(nN), "+s"(Z2));
;         const long L = (long)i * G + c; if (L >= nwg) return false;
;         int wgid = (int)L; { const int q = nwg / NXCD, r = nwg % NXCD, xcd = wgid % NXCD, off = wgid / NXCD; wgid = (xcd < r ? xcd * (q + 1) : r * (q + 1) + (xcd - r) * q) + off; }
;         if (rev) wgid = nwg - 1 - wgid;
;         const int per = nM * nN, z = wgid / per, rem = wgid - z * per;
;         const int nig = WGM * nN, gid = rem / nig, fm = gid * WGM, gsz = (nM - fm) < WGM ? (nM - fm) : WGM, ri = rem - gid * nig;
;         u.pm = fm + (ri % gsz); u.pn = ri / gsz; u.z1 = z / Z2; u.z2 = z - u.z1 * Z2; return true;
; template <class Epi>
; __device__ __forceinline__ void gemm_phase(PG8_LAS unsigned char* lds, PG8_LAS unsigned char* xl, const Gemm g, const Sched& S, const Epi& E, const int wid) {
;     ...
;         const bool has_next = S.next(ui + 1, nxt);
.LBB0_524:
	s_mov_b32 s10, 1
	s_movk_i32 s8, 0xa0
	s_mov_b32 s9, 16
	s_add_i32 s95, s95, 1
	s_mul_i32 s10, s95, s94
	s_mul_hi_u32 s11, s95, s87
	s_add_i32 s11, s11, s10
	s_mul_i32 s10, s95, s87
	s_add_u32 s10, s10, s2
	s_addc_u32 s11, s11, s33
	v_mov_b64_e32 v[0:1], 0xa00
	v_cmp_lt_i64_e64 s[46:47], s[10:11], v[0:1]
	v_mov_b64_e32 v[0:1], 0x9ff
	v_cmp_gt_i64_e64 s[48:49], s[10:11], v[0:1]
	s_and_b64 vcc, exec, s[48:49]
	s_cbranch_vccnz .LBB0_526
	s_ashr_i32 s11, s10, 31
	s_lshr_b32 s11, s11, 29
	s_add_i32 s11, s10, s11
	s_ashr_i32 s30, s11, 3
	s_and_b32 s11, s11, -8
	s_sub_i32 s10, s10, s11
	s_cmp_lt_i32 s10, 0
	s_mul_i32 s31, s8, s9
	s_cselect_b32 s11, s4, 0x140
	s_abs_i32 s31, s31
	s_mul_i32 s10, s10, s11
	s_sub_i32 s11, 0, s31
	s_add_i32 s10, s10, s30
	s_ashr_i32 s30, s10, 31
	s_abs_i32 s10, s10
	s_mov_b32 s36, 0x199999
	s_mul_i32 s11, s11, s36
	s_mul_hi_u32 s11, s36, s11
	s_add_i32 s36, s36, s11
	s_mul_hi_u32 s11, s10, s36
	s_mul_i32 s11, s11, s31
	s_sub_i32 s10, s10, s11
	s_sub_i32 s11, s10, s31
	s_cmp_ge_u32 s10, s31
	s_cselect_b32 s10, s11, s10
	s_sub_i32 s11, s10, s31
	s_cmp_ge_u32 s10, s31
	s_cselect_b32 s10, s11, s10
	s_lshl_b32 s9, s9, 2
	s_abs_i32 s11, s9
	s_xor_b32 s10, s10, s30
	s_sub_i32 s10, s10, s30
	s_sub_i32 s30, 0, s11
	s_abs_i32 s36, s10
	s_xor_b32 s31, s10, s9
	s_ashr_i32 s31, s31, 31
	s_mov_b32 s37, 0x4000000
	s_mul_i32 s30, s30, s37
	s_mul_hi_u32 s30, s37, s30
	s_add_i32 s37, s37, s30
	s_mul_hi_u32 s30, s36, s37
	s_mul_i32 s37, s30, s11
	s_sub_i32 s36, s36, s37
	s_add_i32 s42, s30, 1
	s_sub_i32 s37, s36, s11
	s_cmp_ge_u32 s36, s11
	s_cselect_b32 s30, s42, s30
	s_cselect_b32 s36, s37, s36
	s_add_i32 s37, s30, 1
	s_cmp_ge_u32 s36, s11
	s_cselect_b32 s11, s37, s30
	s_xor_b32 s11, s11, s31
	s_sub_i32 s11, s11, s31
	s_lshl_b32 s30, s11, 2
	s_sub_i32 s8, s8, s30
	s_min_i32 s8, s8, 4
	s_abs_i32 s31, s8
	s_sub_i32 s36, 0, s31
	s_mul_i32 s11, s11, s9
	s_sub_i32 s9, s10, s11
	s_abs_i32 s10, s9
	s_xor_b32 s11, s9, s8
	s_ashr_i32 s11, s11, 31
	s_mov_b32 s37, 0x40000000
	s_mul_i32 s36, s36, s37
	s_mul_hi_u32 s36, s37, s36
	s_add_i32 s37, s37, s36
	s_mul_hi_u32 s36, s10, s37
	s_mul_i32 s37, s36, s31
	s_sub_i32 s10, s10, s37
	s_add_i32 s42, s36, 1
	s_sub_i32 s37, s10, s31
	s_cmp_ge_u32 s10, s31
	s_cselect_b32 s36, s42, s36
	s_cselect_b32 s10, s37, s10
	s_add_i32 s37, s36, 1
	s_cmp_ge_u32 s10, s31
	s_cselect_b32 s10, s37, s36
	s_xor_b32 s10, s10, s11
	s_sub_i32 s58, s10, s11
	s_mul_i32 s8, s58, s8
	s_sub_i32 s8, s9, s8
	s_add_i32 s36, s30, s8

;     __device__ __forceinline__ bool next(int i, Unit& u) const {
;         int nM = this->nM, nN = this->nN, Z2 = this->Z2; asm volatile("" : "+s"(nM), "+s"(nN), "+s"(Z2));
;         const long L = (long)i * G + c; if (L >= nwg) return false;
;         int wgid = (int)L; { const int q = nwg / NXCD, r = nwg % NXCD, xcd = wgid % NXCD, off = wgid / NXCD; wgid = (xcd < r ? xcd * (q + 1) : r * (q + 1) + (xcd - r) * q) + off; }
;         if (rev) wgid = nwg - 1 - wgid;
;         const int per = nM * nN, z = wgid / per, rem = wgid - z * per;
;         const int nig = WGM * nN, gid = rem / nig, fm = gid * WGM, gsz = (nM - fm) < WGM ? (nM - fm) : WGM, ri = rem - gid * nig;
;         u.pm = fm + (ri % gsz); u.pn = ri / gsz; u.z1 = z / Z2; u.z2 = z - u.z1 * Z2; return true;
; template <class Epi>
; __device__ __forceinline__ void gemm_phase(PG8_LAS unsigned char* lds, PG8_LAS unsigned char* xl, const Gemm g, const Sched& S, const Epi& E, const int wid) {
;     ...
;         const bool has_next = S.next(ui + 1, nxt);
.LBB0_684:
	s_mov_b32 s20, 8
	s_mov_b32 s10, 1
	s_movk_i32 s13, 0xa0
	s_add_i32 s88, s88, 1
	s_mul_i32 s10, s88, s87
	s_mul_hi_u32 s11, s88, s0
	s_add_i32 s11, s11, s10
	s_mul_i32 s10, s88, s0
	s_add_u32 s10, s10, s2
	s_addc_u32 s11, s11, s33
	v_cmp_gt_i64_e32 vcc, s[10:11], v[202:203]
	v_cmp_lt_i64_e64 s[48:49], s[10:11], v[200:201]
	s_cbranch_vccnz .LBB0_686
	s_ashr_i32 s11, s10, 31
	s_lshr_b32 s11, s11, 29
	s_add_i32 s11, s10, s11
	s_and_b32 s12, s11, -8
	s_sub_i32 s10, s10, s12
	s_ashr_i32 s11, s11, 3
	s_cmp_lt_i32 s10, 0
	s_mul_i32 s21, s13, s20
	s_cselect_b32 s12, s4, 0xffffff60
	s_abs_i32 s21, s21
	s_mul_i32 s10, s10, s12
	s_sub_i32 s12, 0, s21
	s_sub_i32 s10, s10, s11
	s_addk_i32 s10, 0x4ff
	s_ashr_i32 s11, s10, 31
	s_abs_i32 s10, s10
	s_mov_b32 s30, 0x333333
	s_mul_i32 s12, s12, s30
	s_mul_hi_u32 s12, s30, s12
	s_add_i32 s30, s30, s12
	s_mul_hi_u32 s12, s10, s30
	s_mul_i32 s12, s12, s21
	s_sub_i32 s10, s10, s12
	s_sub_i32 s12, s10, s21
	s_cmp_ge_u32 s10, s21
	s_cselect_b32 s10, s12, s10
	s_sub_i32 s12, s10, s21
	s_cmp_ge_u32 s10, s21
	s_cselect_b32 s10, s12, s10
	s_lshl_b32 s12, s20, 2
	s_abs_i32 s20, s12
	s_xor_b32 s10, s10, s11
	s_sub_i32 s10, s10, s11
	s_sub_i32 s11, 0, s20
	s_abs_i32 s30, s10
	s_xor_b32 s21, s10, s12
	s_ashr_i32 s21, s21, 31
	s_mov_b32 s31, 0x8000000
	s_mul_i32 s11, s11, s31
	s_mul_hi_u32 s11, s31, s11
	s_add_i32 s31, s31, s11
	s_mul_hi_u32 s11, s30, s31
	s_mul_i32 s31, s11, s20
	s_sub_i32 s30, s30, s31
	s_add_i32 s41, s11, 1
	s_sub_i32 s31, s30, s20
	s_cmp_ge_u32 s30, s20
	s_cselect_b32 s11, s41, s11
	s_cselect_b32 s30, s31, s30
	s_add_i32 s31, s11, 1
	s_cmp_ge_u32 s30, s20
	s_cselect_b32 s11, s31, s11
	s_xor_b32 s11, s11, s21
	s_sub_i32 s11, s11, s21
	s_lshl_b32 s20, s11, 2
	s_sub_i32 s13, s13, s20
	s_min_i32 s13, s13, 4
	s_abs_i32 s21, s13
	s_sub_i32 s30, 0, s21
	s_mul_i32 s11, s11, s12
	s_sub_i32 s10, s10, s11
	s_abs_i32 s11, s10
	s_xor_b32 s12, s10, s13
	s_ashr_i32 s12, s12, 31
	s_mov_b32 s31, 0x40000000
	s_mul_i32 s30, s30, s31
	s_mul_hi_u32 s30, s31, s30
	s_add_i32 s31, s31, s30
	s_mul_hi_u32 s30, s11, s31
	s_mul_i32 s31, s30, s21
	s_sub_i32 s11, s11, s31
	s_add_i32 s41, s30, 1
	s_sub_i32 s31, s11, s21
	s_cmp_ge_u32 s11, s21
	s_cselect_b32 s30, s41, s30
	s_cselect_b32 s11, s31, s11
	s_add_i32 s31, s30, 1
	s_cmp_ge_u32 s11, s21
	s_cselect_b32 s11, s31, s30
	s_xor_b32 s11, s11, s12
	s_sub_i32 s12, s11, s12
	s_mul_i32 s11, s12, s13
	s_sub_i32 s10, s10, s11
	s_add_i32 s89, s20, s10

;     __device__ __forceinline__ bool next(int i, Unit& u) const {
;         int nM = this->nM, nN = this->nN, Z2 = this->Z2; asm volatile("" : "+s"(nM), "+s"(nN), "+s"(Z2));
;         const long L = (long)i * G + c; if (L >= nwg) return false;
;         int wgid = (int)L; { const int q = nwg / NXCD, r = nwg % NXCD, xcd = wgid % NXCD, off = wgid / NXCD; wgid = (xcd < r ? xcd * (q + 1) : r * (q + 1) + (xcd - r) * q) + off; }
;         if (rev) wgid = nwg - 1 - wgid;
;         const int per = nM * nN, z = wgid / per, rem = wgid - z * per;
;         const int nig = WGM * nN, gid = rem / nig, fm = gid * WGM, gsz = (nM - fm) < WGM ? (nM - fm) : WGM, ri = rem - gid * nig;
;         u.pm = fm + (ri % gsz); u.pn = ri / gsz; u.z1 = z / Z2; u.z2 = z - u.z1 * Z2; return true;
; template <class Epi>
; __device__ __forceinline__ void gemm_phase(PG8_LAS unsigned char* lds, PG8_LAS unsigned char* xl, const Gemm g, const Sched& S, const Epi& E, const int wid) {
;     ...
;     if (!S.next(0, cur)) return;
.LBB0_752:
	v_readlane_b32 s8, v253, 0
	v_readlane_b32 s9, v253, 1
	v_readlane_b32 s0, v252, 41
	s_waitcnt lgkmcnt(0)
	s_barrier
	s_load_dwordx2 s[30:31], s[8:9], 0xd8
	v_readlane_b32 s4, v252, 46
	v_readlane_b32 s5, v252, 47
	s_mov_b32 s8, 8
	s_mov_b32 s9, 1
	s_movk_i32 s1, 0xa0
	s_and_b64 vcc, exec, s[4:5]
	v_mbcnt_lo_u32_b32 v8, -1, 0
	v_mbcnt_hi_u32_b32 v8, -1, v8
	s_cbranch_vccnz .LBB0_754
	s_mul_i32 s9, s1, s8
	s_abs_i32 s9, s9
	s_sub_i32 s10, 0, s9
	v_readlane_b32 s4, v254, 63
	s_nop 0
	s_mov_b32 s11, 0x333333
	s_mul_i32 s10, s10, s11
	s_mul_hi_u32 s10, s11, s10
	s_add_i32 s11, s11, s10
	s_mul_hi_u32 s10, s4, s11
	s_mul_i32 s10, s10, s9
	s_sub_i32 s10, s4, s10
	s_sub_i32 s11, s10, s9
	s_cmp_ge_u32 s10, s9
	s_cselect_b32 s10, s11, s10
	s_sub_i32 s11, s10, s9
	s_cmp_ge_u32 s10, s9
	s_cselect_b32 s9, s11, s10
	s_lshl_b32 s8, s8, 2
	s_abs_i32 s10, s8
	v_readlane_b32 s4, v254, 61
	s_sub_i32 s11, 0, s10
	s_xor_b32 s9, s9, s4
	s_sub_i32 s9, s9, s4
	s_abs_i32 s13, s9
	s_xor_b32 s12, s9, s8
	s_ashr_i32 s12, s12, 31
	s_mov_b32 s20, 0x8000000
	s_mul_i32 s11, s11, s20
	s_mul_hi_u32 s11, s20, s11
	s_add_i32 s20, s20, s11
	s_mul_hi_u32 s11, s13, s20
	s_mul_i32 s20, s11, s10
	s_sub_i32 s13, s13, s20
	s_add_i32 s21, s11, 1
	s_sub_i32 s20, s13, s10
	s_cmp_ge_u32 s13, s10
	s_cselect_b32 s11, s21, s11
	s_cselect_b32 s13, s20, s13
	s_add_i32 s20, s11, 1
	s_cmp_ge_u32 s13, s10
	s_cselect_b32 s10, s20, s11
	s_xor_b32 s10, s10, s12
	s_sub_i32 s10, s10, s12
	s_lshl_b32 s11, s10, 2
	s_sub_i32 s1, s1, s11
	s_min_i32 s1, s1, 4
	s_abs_i32 s12, s1
	s_sub_i32 s13, 0, s12
	s_mul_i32 s10, s10, s8
	s_sub_i32 s8, s9, s10
	s_abs_i32 s9, s8
	s_xor_b32 s10, s8, s1
	s_ashr_i32 s10, s10, 31
	s_mov_b32 s20, 0x40000000
	s_mul_i32 s13, s13, s20
	s_mul_hi_u32 s13, s20, s13
	s_add_i32 s20, s20, s13
	s_mul_hi_u32 s13, s9, s20
	s_mul_i32 s20, s13, s12
	s_sub_i32 s9, s9, s20
	s_add_i32 s21, s13, 1
	s_sub_i32 s20, s9, s12
	s_cmp_ge_u32 s9, s12
	s_cselect_b32 s13, s21, s13
	s_cselect_b32 s9, s20, s9
	s_add_i32 s20, s13, 1
	s_cmp_ge_u32 s9, s12
	s_cselect_b32 s9, s20, s13
	s_xor_b32 s9, s9, s10
	s_sub_i32 s12, s9, s10
	s_mul_i32 s1, s12, s1
	s_sub_i32 s1, s8, s1
	s_add_i32 s20, s11, s1

;     __device__ __forceinline__ bool next(int i, Unit& u) const {
;         int nM = this->nM, nN = this->nN, Z2 = this->Z2; asm volatile("" : "+s"(nM), "+s"(nN), "+s"(Z2));
;         const long L = (long)i * G + c; if (L >= nwg) return false;
;         int wgid = (int)L; { const int q = nwg / NXCD, r = nwg % NXCD, xcd = wgid % NXCD, off = wgid / NXCD; wgid = (xcd < r ? xcd * (q + 1) : r * (q + 1) + (xcd - r) * q) + off; }
;         if (rev) wgid = nwg - 1 - wgid;
;         const int per = nM * nN, z = wgid / per, rem = wgid - z * per;
;         const int nig = WGM * nN, gid = rem / nig, fm = gid * WGM, gsz = (nM - fm) < WGM ? (nM - fm) : WGM, ri = rem - gid * nig;
;         u.pm = fm + (ri % gsz); u.pn = ri / gsz; u.z1 = z / Z2; u.z2 = z - u.z1 * Z2; return true;
; template <class Epi>
; __device__ __forceinline__ void gemm_phase(PG8_LAS unsigned char* lds, PG8_LAS unsigned char* xl, const Gemm g, const Sched& S, const Epi& E, const int wid) {
;     ...
;         const bool has_next = S.next(ui + 1, nxt);
.LBB0_760:
	s_mov_b32 s9, 8
	s_mov_b32 s10, 1
	s_movk_i32 s8, 0xa0
	s_add_i32 s69, s69, 1
	s_mul_i32 s10, s69, s68
	s_mul_hi_u32 s11, s69, s0
	s_add_i32 s11, s11, s10
	s_mul_i32 s10, s69, s0
	s_add_u32 s10, s10, s2
	s_addc_u32 s11, s11, s33
	v_cmp_gt_i64_e32 vcc, s[10:11], v[202:203]
	v_cmp_lt_i64_e64 s[48:49], s[10:11], v[200:201]
	s_cbranch_vccnz .LBB0_762
	s_ashr_i32 s11, s10, 31
	s_lshr_b32 s11, s11, 29
	s_add_i32 s11, s10, s11
	s_ashr_i32 s13, s11, 3
	s_and_b32 s11, s11, -8
	s_sub_i32 s10, s10, s11
	s_cmp_lt_i32 s10, 0
	s_movk_i32 s4, 0xa1
	s_mul_i32 s21, s8, s9
	s_cselect_b32 s11, s4, 0xa0
	s_abs_i32 s21, s21
	s_mul_i32 s10, s10, s11
	s_sub_i32 s11, 0, s21
	s_add_i32 s10, s10, s13
	s_ashr_i32 s13, s10, 31
	s_abs_i32 s10, s10
	s_mov_b32 s30, 0x333333
	s_mul_i32 s11, s11, s30
	s_mul_hi_u32 s11, s30, s11
	s_add_i32 s30, s30, s11
	s_mul_hi_u32 s11, s10, s30
	s_mul_i32 s11, s11, s21
	s_sub_i32 s10, s10, s11
	s_sub_i32 s11, s10, s21
	s_cmp_ge_u32 s10, s21
	s_cselect_b32 s10, s11, s10
	s_sub_i32 s11, s10, s21
	s_cmp_ge_u32 s10, s21
	s_cselect_b32 s10, s11, s10
	s_lshl_b32 s9, s9, 2
	s_abs_i32 s11, s9
	s_xor_b32 s10, s10, s13
	s_sub_i32 s10, s10, s13
	s_sub_i32 s13, 0, s11
	s_abs_i32 s30, s10
	s_xor_b32 s21, s10, s9
	s_ashr_i32 s21, s21, 31
	s_mov_b32 s31, 0x8000000
	s_mul_i32 s13, s13, s31
	s_mul_hi_u32 s13, s31, s13
	s_add_i32 s31, s31, s13
	s_mul_hi_u32 s13, s30, s31
	s_mul_i32 s31, s13, s11
	s_sub_i32 s30, s30, s31
	s_add_i32 s36, s13, 1
	s_sub_i32 s31, s30, s11
	s_cmp_ge_u32 s30, s11
	s_cselect_b32 s13, s36, s13
	s_cselect_b32 s30, s31, s30
	s_add_i32 s31, s13, 1
	s_cmp_ge_u32 s30, s11
	s_cselect_b32 s11, s31, s13
	s_xor_b32 s11, s11, s21
	s_sub_i32 s11, s11, s21
	s_lshl_b32 s13, s11, 2
	s_sub_i32 s8, s8, s13
	s_min_i32 s8, s8, 4
	s_abs_i32 s21, s8
	s_sub_i32 s30, 0, s21
	s_mul_i32 s11, s11, s9
	s_sub_i32 s9, s10, s11
	s_abs_i32 s10, s9
	s_xor_b32 s11, s9, s8
	s_ashr_i32 s11, s11, 31
	s_mov_b32 s31, 0x40000000
	s_mul_i32 s30, s30, s31
	s_mul_hi_u32 s30, s31, s30
	s_add_i32 s31, s31, s30
	s_mul_hi_u32 s30, s10, s31
	s_mul_i32 s31, s30, s21
	s_sub_i32 s10, s10, s31
	s_add_i32 s36, s30, 1
	s_sub_i32 s31, s10, s21
	s_cmp_ge_u32 s10, s21
	s_cselect_b32 s30, s36, s30
	s_cselect_b32 s10, s31, s10
	s_add_i32 s31, s30, 1
	s_cmp_ge_u32 s10, s21
	s_cselect_b32 s10, s31, s30
	s_xor_b32 s10, s10, s11
	s_sub_i32 s30, s10, s11
	s_mul_i32 s8, s30, s8
	s_sub_i32 s8, s9, s8
	s_add_i32 s70, s13, s8

;     __device__ __forceinline__ bool next(int i, Unit& u) const {
;         int nM = this->nM, nN = this->nN, Z2 = this->Z2; asm volatile("" : "+s"(nM), "+s"(nN), "+s"(Z2));
;         const long L = (long)i * G + c; if (L >= nwg) return false;
;         int wgid = (int)L; { const int q = nwg / NXCD, r = nwg % NXCD, xcd = wgid % NXCD, off = wgid / NXCD; wgid = (xcd < r ? xcd * (q + 1) : r * (q + 1) + (xcd - r) * q) + off; }
;         if (rev) wgid = nwg - 1 - wgid;
;         const int per = nM * nN, z = wgid / per, rem = wgid - z * per;
;         const int nig = WGM * nN, gid = rem / nig, fm = gid * WGM, gsz = (nM - fm) < WGM ? (nM - fm) : WGM, ri = rem - gid * nig;
;         u.pm = fm + (ri % gsz); u.pn = ri / gsz; u.z1 = z / Z2; u.z2 = z - u.z1 * Z2; return true;
; template <class Epi>
; __device__ __forceinline__ void gemm_phase(PG8_LAS unsigned char* lds, PG8_LAS unsigned char* xl, const Gemm g, const Sched& S, const Epi& E, const int wid) {
;     ...
;     if (!S.next(0, cur)) return;
.LBB0_844:
	v_readlane_b32 s36, v253, 0
	v_readlane_b32 s37, v253, 1
	v_readlane_b32 s0, v252, 41
	s_waitcnt lgkmcnt(0)
	s_barrier
	s_load_dwordx2 s[30:31], s[36:37], 0xd8
	v_readlane_b32 s4, v252, 54
	v_readlane_b32 s5, v252, 55
	s_mov_b32 s8, 8
	s_mov_b32 s1, 1
	s_mov_b32 s9, 4
	s_and_b64 vcc, exec, s[4:5]
	v_mbcnt_lo_u32_b32 v8, -1, 0
	v_mbcnt_hi_u32_b32 v8, -1, v8
	s_cbranch_vccnz .LBB0_846
	s_mul_i32 s10, s8, s9
	s_abs_i32 s11, s10
	s_sub_i32 s13, 0, s11
	s_ashr_i32 s12, s10, 31
	v_readlane_b32 s4, v252, 0
	s_xor_b32 s12, s4, s12
	v_readlane_b32 s4, v252, 2
	s_mov_b32 s20, 0x8000000
	s_mul_i32 s13, s13, s20
	s_mul_hi_u32 s13, s20, s13
	s_add_i32 s20, s20, s13
	s_mul_hi_u32 s13, s4, s20
	s_mul_i32 s20, s13, s11
	s_sub_i32 s20, s4, s20
	s_add_i32 s21, s13, 1
	s_sub_i32 s40, s20, s11
	s_cmp_ge_u32 s20, s11
	s_cselect_b32 s13, s21, s13
	s_cselect_b32 s20, s40, s20
	s_add_i32 s21, s13, 1
	s_cmp_ge_u32 s20, s11
	s_cselect_b32 s11, s21, s13
	s_lshl_b32 s9, s9, 2
	s_abs_i32 s13, s9
	s_xor_b32 s11, s11, s12
	s_sub_i32 s11, s11, s12
	s_sub_i32 s12, 0, s13
	s_mul_i32 s10, s11, s10
	v_readlane_b32 s4, v252, 1
	s_sub_i32 s10, s4, s10
	s_abs_i32 s21, s10
	s_xor_b32 s20, s10, s9
	s_ashr_i32 s20, s20, 31
	s_mov_b32 s40, 0x10000000
	s_mul_i32 s12, s12, s40
	s_mul_hi_u32 s12, s40, s12
	s_add_i32 s40, s40, s12
	s_mul_hi_u32 s12, s21, s40
	s_mul_i32 s40, s12, s13
	s_sub_i32 s21, s21, s40
	s_add_i32 s41, s12, 1
	s_sub_i32 s40, s21, s13
	s_cmp_ge_u32 s21, s13
	s_cselect_b32 s12, s41, s12
	s_cselect_b32 s21, s40, s21
	s_add_i32 s40, s12, 1
	s_cmp_ge_u32 s21, s13
	s_cselect_b32 s12, s40, s12
	s_xor_b32 s12, s12, s20
	s_sub_i32 s12, s12, s20
	s_lshl_b32 s13, s12, 2
	s_sub_i32 s8, s8, s13
	s_min_i32 s8, s8, 4
	s_abs_i32 s20, s8
	s_sub_i32 s21, 0, s20
	s_mul_i32 s12, s12, s9
	s_sub_i32 s9, s10, s12
	s_abs_i32 s10, s9
	s_xor_b32 s12, s9, s8
	s_ashr_i32 s12, s12, 31
	s_mov_b32 s40, 0x40000000
	s_mul_i32 s21, s21, s40
	s_mul_hi_u32 s21, s40, s21
	s_add_i32 s40, s40, s21
	s_mul_hi_u32 s21, s10, s40
	s_mul_i32 s40, s21, s20
	s_sub_i32 s10, s10, s40
	s_add_i32 s41, s21, 1
	s_sub_i32 s40, s10, s20
	s_cmp_ge_u32 s10, s20
	s_cselect_b32 s21, s41, s21
	s_cselect_b32 s10, s40, s10
	s_add_i32 s40, s21, 1
	s_cmp_ge_u32 s10, s20
	s_cselect_b32 s10, s40, s21
	s_abs_i32 s20, s1
	s_xor_b32 s10, s10, s12
	s_sub_i32 s42, s10, s12
	s_mul_i32 s8, s42, s8
	s_sub_i32 s8, s9, s8
	s_sub_i32 s21, 0, s20
	s_add_i32 s52, s13, s8
	s_xor_b32 s1, s11, s1
	s_abs_i32 s11, s11
	s_ashr_i32 s1, s1, 31
	s_mov_b32 s8, 0xffffffff
	s_mul_i32 s21, s21, s8
	s_mul_hi_u32 s9, s8, s21
	s_add_i32 s8, s8, s9
	s_mul_hi_u32 s8, s11, s8
	s_mul_i32 s9, s8, s20
	s_sub_i32 s9, s11, s9
	s_add_i32 s10, s8, 1
	s_sub_i32 s11, s9, s20
	s_cmp_ge_u32 s9, s20
	s_cselect_b32 s8, s10, s8
	s_cselect_b32 s9, s11, s9
	s_add_i32 s10, s8, 1
	s_cmp_ge_u32 s9, s20
	s_cselect_b32 s8, s10, s8
	s_xor_b32 s8, s8, s1
	s_sub_i32 s56, s8, s1

;     __device__ __forceinline__ bool next(int i, Unit& u) const {
;         int nM = this->nM, nN = this->nN, Z2 = this->Z2; asm volatile("" : "+s"(nM), "+s"(nN), "+s"(Z2));
;         const long L = (long)i * G + c; if (L >= nwg) return false;
;         int wgid = (int)L; { const int q = nwg / NXCD, r = nwg % NXCD, xcd = wgid % NXCD, off = wgid / NXCD; wgid = (xcd < r ? xcd * (q + 1) : r * (q + 1) + (xcd - r) * q) + off; }
;         if (rev) wgid = nwg - 1 - wgid;
;         const int per = nM * nN, z = wgid / per, rem = wgid - z * per;
;         const int nig = WGM * nN, gid = rem / nig, fm = gid * WGM, gsz = (nM - fm) < WGM ? (nM - fm) : WGM, ri = rem - gid * nig;
;         u.pm = fm + (ri % gsz); u.pn = ri / gsz; u.z1 = z / Z2; u.z2 = z - u.z1 * Z2; return true;
; template <class Epi>
; __device__ __forceinline__ void gemm_phase(PG8_LAS unsigned char* lds, PG8_LAS unsigned char* xl, const Gemm g, const Sched& S, const Epi& E, const int wid) {
;     ...
;         const bool has_next = S.next(ui + 1, nxt);
.LBB0_852:
	s_add_i32 s68, s68, 1
	s_mul_i32 s10, s68, s97
	s_mul_hi_u32 s11, s68, s0
	s_add_i32 s11, s11, s10
	s_mul_i32 s10, s68, s0
	s_add_u32 s10, s10, s2
	s_addc_u32 s11, s11, s33
	v_cmp_gt_i64_e32 vcc, s[10:11], v[198:199]
	s_mov_b32 s9, 8
	s_mov_b32 s8, 1
	s_mov_b32 s13, 4
	v_cmp_lt_i64_e64 s[46:47], s[10:11], v[196:197]
	s_cbranch_vccnz .LBB0_854
	s_ashr_i32 s11, s10, 31
	s_lshr_b32 s11, s11, 29
	s_add_i32 s11, s10, s11
	s_and_b32 s12, s11, -8
	s_sub_i32 s10, s10, s12
	s_ashr_i32 s11, s11, 3
	s_cmp_lt_i32 s10, 0
	s_mul_i32 s20, s9, s13
	s_cselect_b32 s12, s4, 0xffffffb0
	s_abs_i32 s21, s20
	s_mul_i32 s10, s10, s12
	s_sub_i32 s43, 0, s21
	s_sub_i32 s10, s10, s11
	s_addk_i32 s10, 0x27f
	s_abs_i32 s12, s10
	s_xor_b32 s11, s10, s20
	s_ashr_i32 s11, s11, 31
	s_mov_b32 s44, 0x8000000
	s_mul_i32 s43, s43, s44
	s_mul_hi_u32 s43, s44, s43
	s_add_i32 s44, s44, s43
	s_mul_hi_u32 s43, s12, s44
	s_mul_i32 s44, s43, s21
	s_sub_i32 s12, s12, s44
	s_add_i32 s44, s43, 1
	s_sub_i32 s45, s12, s21
	s_cmp_ge_u32 s12, s21
	s_cselect_b32 s43, s44, s43
	s_cselect_b32 s12, s45, s12
	s_add_i32 s44, s43, 1
	s_cmp_ge_u32 s12, s21
	s_cselect_b32 s12, s44, s43
	s_lshl_b32 s13, s13, 2
	s_abs_i32 s21, s13
	s_xor_b32 s12, s12, s11
	s_sub_i32 s11, s12, s11
	s_sub_i32 s43, 0, s21
	s_mul_i32 s12, s11, s20
	s_sub_i32 s10, s10, s12
	s_abs_i32 s20, s10
	s_xor_b32 s12, s10, s13
	s_ashr_i32 s12, s12, 31
	s_mov_b32 s44, 0x10000000
	s_mul_i32 s43, s43, s44
	s_mul_hi_u32 s43, s44, s43
	s_add_i32 s44, s44, s43
	s_mul_hi_u32 s43, s20, s44
	s_mul_i32 s44, s43, s21
	s_sub_i32 s20, s20, s44
	s_add_i32 s44, s43, 1
	s_sub_i32 s45, s20, s21
	s_cmp_ge_u32 s20, s21
	s_cselect_b32 s43, s44, s43
	s_cselect_b32 s20, s45, s20
	s_add_i32 s44, s43, 1
	s_cmp_ge_u32 s20, s21
	s_cselect_b32 s20, s44, s43
	s_xor_b32 s20, s20, s12
	s_sub_i32 s12, s20, s12
	s_lshl_b32 s20, s12, 2
	s_sub_i32 s9, s9, s20
	s_min_i32 s9, s9, 4
	s_abs_i32 s21, s9
	s_sub_i32 s43, 0, s21
	s_mul_i32 s12, s12, s13
	s_sub_i32 s10, s10, s12
	s_abs_i32 s13, s10
	s_xor_b32 s12, s10, s9
	s_ashr_i32 s12, s12, 31
	s_mov_b32 s44, 0x40000000
	s_mul_i32 s43, s43, s44
	s_mul_hi_u32 s43, s44, s43
	s_add_i32 s44, s44, s43
	s_mul_hi_u32 s43, s13, s44
	s_mul_i32 s44, s43, s21
	s_sub_i32 s13, s13, s44
	s_add_i32 s44, s43, 1
	s_sub_i32 s45, s13, s21
	s_cmp_ge_u32 s13, s21
	s_cselect_b32 s43, s44, s43
	s_cselect_b32 s13, s45, s13
	s_add_i32 s44, s43, 1
	s_cmp_ge_u32 s13, s21
	s_cselect_b32 s13, s44, s43
	s_abs_i32 s21, s8
	s_xor_b32 s13, s13, s12
	s_sub_i32 s12, s13, s12
	s_mul_i32 s9, s12, s9
	s_sub_i32 s9, s10, s9
	s_add_i32 s76, s20, s9
	s_xor_b32 s8, s11, s8
	s_abs_i32 s9, s11
	s_sub_i32 s10, 0, s21
	s_ashr_i32 s8, s8, 31
	s_mov_b32 s11, 0xffffffff
	s_mul_i32 s10, s10, s11
	s_mul_hi_u32 s10, s11, s10
	s_add_i32 s11, s11, s10
	s_mul_hi_u32 s10, s9, s11
	s_mul_i32 s11, s10, s21
	s_sub_i32 s9, s9, s11
	s_add_i32 s11, s10, 1
	s_sub_i32 s13, s9, s21
	s_cmp_ge_u32 s9, s21
	s_cselect_b32 s10, s11, s10
	s_cselect_b32 s9, s13, s9
	s_add_i32 s11, s10, 1
	s_cmp_ge_u32 s9, s21
	s_cselect_b32 s9, s11, s10
	s_xor_b32 s9, s9, s8
	s_sub_i32 s60, s9, s8

;     __device__ __forceinline__ bool next(int i, Unit& u) const {
;         int nM = this->nM, nN = this->nN, Z2 = this->Z2; asm volatile("" : "+s"(nM), "+s"(nN), "+s"(Z2));
;         const long L = (long)i * G + c; if (L >= nwg) return false;
;         int wgid = (int)L; { const int q = nwg / NXCD, r = nwg % NXCD, xcd = wgid % NXCD, off = wgid / NXCD; wgid = (xcd < r ? xcd * (q + 1) : r * (q + 1) + (xcd - r) * q) + off; }
;         if (rev) wgid = nwg - 1 - wgid;
;         const int per = nM * nN, z = wgid / per, rem = wgid - z * per;
;         const int nig = WGM * nN, gid = rem / nig, fm = gid * WGM, gsz = (nM - fm) < WGM ? (nM - fm) : WGM, ri = rem - gid * nig;
;         u.pm = fm + (ri % gsz); u.pn = ri / gsz; u.z1 = z / Z2; u.z2 = z - u.z1 * Z2; return true;
; template <class Epi>
; __device__ __forceinline__ void gemm_phase(PG8_LAS unsigned char* lds, PG8_LAS unsigned char* xl, const Gemm g, const Sched& S, const Epi& E, const int wid) {
;     ...
;     if (!S.next(0, cur)) return;
.LBB0_944:
	v_readlane_b32 s8, v253, 0
	v_readlane_b32 s9, v253, 1
	v_readlane_b32 s0, v252, 41
	s_waitcnt lgkmcnt(0)
	s_barrier
	s_load_dwordx2 s[36:37], s[8:9], 0xd8
	v_readlane_b32 s4, v252, 46
	v_readlane_b32 s5, v252, 47
	s_mov_b32 s8, 8
	s_mov_b32 s9, 8
	s_mov_b32 s1, 1
	s_and_b64 vcc, exec, s[4:5]
	v_mbcnt_lo_u32_b32 v8, -1, 0
	v_mbcnt_hi_u32_b32 v8, -1, v8
	s_cbranch_vccnz .LBB0_946
	s_mul_i32 s10, s8, s9
	s_abs_i32 s11, s10
	s_sub_i32 s13, 0, s11
	s_ashr_i32 s12, s10, 31
	v_readlane_b32 s4, v254, 61
	s_xor_b32 s12, s4, s12
	v_readlane_b32 s4, v254, 63
	s_mov_b32 s20, 0x4000000
	s_mul_i32 s13, s13, s20
	s_mul_hi_u32 s13, s20, s13
	s_add_i32 s20, s20, s13
	s_mul_hi_u32 s13, s4, s20
	s_mul_i32 s20, s13, s11
	s_sub_i32 s20, s4, s20
	s_add_i32 s21, s13, 1
	s_sub_i32 s30, s20, s11
	s_cmp_ge_u32 s20, s11
	s_cselect_b32 s13, s21, s13
	s_cselect_b32 s20, s30, s20
	s_add_i32 s21, s13, 1
	s_cmp_ge_u32 s20, s11
	s_cselect_b32 s11, s21, s13
	s_lshl_b32 s9, s9, 2
	s_abs_i32 s13, s9
	s_xor_b32 s11, s11, s12
	s_sub_i32 s11, s11, s12
	s_sub_i32 s12, 0, s13
	s_mul_i32 s10, s11, s10
	v_readlane_b32 s4, v254, 62
	s_sub_i32 s10, s4, s10
	s_abs_i32 s21, s10
	s_xor_b32 s20, s10, s9
	s_ashr_i32 s20, s20, 31
	s_mov_b32 s30, 0x8000000
	s_mul_i32 s12, s12, s30
	s_mul_hi_u32 s12, s30, s12
	s_add_i32 s30, s30, s12
	s_mul_hi_u32 s12, s21, s30
	s_mul_i32 s30, s12, s13
	s_sub_i32 s21, s21, s30
	s_add_i32 s31, s12, 1
	s_sub_i32 s30, s21, s13
	s_cmp_ge_u32 s21, s13
	s_cselect_b32 s12, s31, s12
	s_cselect_b32 s21, s30, s21
	s_add_i32 s30, s12, 1
	s_cmp_ge_u32 s21, s13
	s_cselect_b32 s12, s30, s12
	s_xor_b32 s12, s12, s20
	s_sub_i32 s12, s12, s20
	s_lshl_b32 s13, s12, 2
	s_sub_i32 s8, s8, s13
	s_min_i32 s8, s8, 4
	s_abs_i32 s20, s8
	s_sub_i32 s21, 0, s20
	s_mul_i32 s12, s12, s9
	s_sub_i32 s9, s10, s12
	s_abs_i32 s10, s9
	s_xor_b32 s12, s9, s8
	s_ashr_i32 s12, s12, 31
	s_mov_b32 s30, 0x40000000
	s_mul_i32 s21, s21, s30
	s_mul_hi_u32 s21, s30, s21
	s_add_i32 s30, s30, s21
	s_mul_hi_u32 s21, s10, s30
	s_mul_i32 s30, s21, s20
	s_sub_i32 s10, s10, s30
	s_add_i32 s31, s21, 1
	s_sub_i32 s30, s10, s20
	s_cmp_ge_u32 s10, s20
	s_cselect_b32 s21, s31, s21
	s_cselect_b32 s10, s30, s10
	s_add_i32 s30, s21, 1
	s_cmp_ge_u32 s10, s20
	s_cselect_b32 s10, s30, s21
	s_abs_i32 s21, s1
	s_xor_b32 s10, s10, s12
	s_sub_i32 s12, s10, s12
	s_mul_i32 s8, s12, s8
	s_sub_i32 s8, s9, s8
	s_sub_i32 s30, 0, s21
	s_add_i32 s20, s13, s8
	s_xor_b32 s1, s11, s1
	s_abs_i32 s11, s11
	s_ashr_i32 s1, s1, 31
	s_mov_b32 s8, 0xffffffff
	s_mul_i32 s30, s30, s8
	s_mul_hi_u32 s9, s8, s30
	s_add_i32 s8, s8, s9
	s_mul_hi_u32 s8, s11, s8
	s_mul_i32 s9, s8, s21
	s_sub_i32 s9, s11, s9
	s_add_i32 s10, s8, 1
	s_sub_i32 s11, s9, s21
	s_cmp_ge_u32 s9, s21
	s_cselect_b32 s8, s10, s8
	s_cselect_b32 s9, s11, s9
	s_add_i32 s10, s8, 1
	s_cmp_ge_u32 s9, s21
	s_cselect_b32 s8, s10, s8
	s_xor_b32 s8, s8, s1
	s_sub_i32 s30, s8, s1

;     __device__ __forceinline__ bool next(int i, Unit& u) const {
;         int nM = this->nM, nN = this->nN, Z2 = this->Z2; asm volatile("" : "+s"(nM), "+s"(nN), "+s"(Z2));
;         const long L = (long)i * G + c; if (L >= nwg) return false;
;         int wgid = (int)L; { const int q = nwg / NXCD, r = nwg % NXCD, xcd = wgid % NXCD, off = wgid / NXCD; wgid = (xcd < r ? xcd * (q + 1) : r * (q + 1) + (xcd - r) * q) + off; }
;         if (rev) wgid = nwg - 1 - wgid;
;         const int per = nM * nN, z = wgid / per, rem = wgid - z * per;
;         const int nig = WGM * nN, gid = rem / nig, fm = gid * WGM, gsz = (nM - fm) < WGM ? (nM - fm) : WGM, ri = rem - gid * nig;
;         u.pm = fm + (ri % gsz); u.pn = ri / gsz; u.z1 = z / Z2; u.z2 = z - u.z1 * Z2; return true;
; template <class Epi>
; __device__ __forceinline__ void gemm_phase(PG8_LAS unsigned char* lds, PG8_LAS unsigned char* xl, const Gemm g, const Sched& S, const Epi& E, const int wid) {
;     ...
;         const bool has_next = S.next(ui + 1, nxt);
.LBB0_952:
	s_add_i32 s90, s90, 1
	s_mul_i32 s10, s90, s89
	s_mul_hi_u32 s11, s90, s0
	s_add_i32 s11, s11, s10
	s_mul_i32 s10, s90, s0
	s_add_u32 s10, s10, s2
	s_addc_u32 s11, s11, s33
	v_cmp_gt_i64_e32 vcc, s[10:11], v[202:203]
	s_mov_b32 s9, 8
	s_mov_b32 s13, 8
	s_mov_b32 s8, 1
	v_cmp_lt_i64_e64 s[46:47], s[10:11], v[200:201]
	s_cbranch_vccnz .LBB0_954
	s_ashr_i32 s11, s10, 31
	s_lshr_b32 s11, s11, 29
	s_add_i32 s11, s10, s11
	s_ashr_i32 s21, s11, 3
	s_and_b32 s11, s11, -8
	s_sub_i32 s10, s10, s11
	s_cmp_lt_i32 s10, 0
	s_movk_i32 s4, 0xa1
	s_mul_i32 s31, s9, s13
	s_cselect_b32 s11, s4, 0xa0
	s_abs_i32 s36, s31
	s_mul_i32 s10, s10, s11
	s_sub_i32 s11, 0, s36
	s_add_i32 s10, s10, s21
	s_abs_i32 s37, s10
	s_xor_b32 s21, s10, s31
	s_ashr_i32 s21, s21, 31
	s_mov_b32 s42, 0x4000000
	s_mul_i32 s11, s11, s42
	s_mul_hi_u32 s11, s42, s11
	s_add_i32 s42, s42, s11
	s_mul_hi_u32 s11, s37, s42
	s_mul_i32 s42, s11, s36
	s_sub_i32 s37, s37, s42
	s_add_i32 s42, s11, 1
	s_sub_i32 s43, s37, s36
	s_cmp_ge_u32 s37, s36
	s_cselect_b32 s11, s42, s11
	s_cselect_b32 s37, s43, s37
	s_add_i32 s42, s11, 1
	s_cmp_ge_u32 s37, s36
	s_cselect_b32 s11, s42, s11
	s_lshl_b32 s13, s13, 2
	s_abs_i32 s36, s13
	s_xor_b32 s11, s11, s21
	s_sub_i32 s11, s11, s21
	s_sub_i32 s37, 0, s36
	s_mul_i32 s21, s11, s31
	s_sub_i32 s10, s10, s21
	s_abs_i32 s31, s10
	s_xor_b32 s21, s10, s13
	s_ashr_i32 s21, s21, 31
	s_mov_b32 s42, 0x8000000
	s_mul_i32 s37, s37, s42
	s_mul_hi_u32 s37, s42, s37
	s_add_i32 s42, s42, s37
	s_mul_hi_u32 s37, s31, s42
	s_mul_i32 s42, s37, s36
	s_sub_i32 s31, s31, s42
	s_add_i32 s42, s37, 1
	s_sub_i32 s43, s31, s36
	s_cmp_ge_u32 s31, s36
	s_cselect_b32 s37, s42, s37
	s_cselect_b32 s31, s43, s31
	s_add_i32 s42, s37, 1
	s_cmp_ge_u32 s31, s36
	s_cselect_b32 s31, s42, s37
	s_xor_b32 s31, s31, s21
	s_sub_i32 s21, s31, s21
	s_lshl_b32 s31, s21, 2
	s_sub_i32 s9, s9, s31
	s_min_i32 s9, s9, 4
	s_abs_i32 s36, s9
	s_sub_i32 s37, 0, s36
	s_mul_i32 s21, s21, s13
	s_sub_i32 s10, s10, s21
	s_abs_i32 s21, s10
	s_xor_b32 s13, s10, s9
	s_ashr_i32 s13, s13, 31
	s_mov_b32 s42, 0x40000000
	s_mul_i32 s37, s37, s42
	s_mul_hi_u32 s37, s42, s37
	s_add_i32 s42, s42, s37
	s_mul_hi_u32 s37, s21, s42
	s_mul_i32 s42, s37, s36
	s_sub_i32 s21, s21, s42
	s_add_i32 s42, s37, 1
	s_sub_i32 s43, s21, s36
	s_cmp_ge_u32 s21, s36
	s_cselect_b32 s37, s42, s37
	s_cselect_b32 s21, s43, s21
	s_add_i32 s42, s37, 1
	s_cmp_ge_u32 s21, s36
	s_cselect_b32 s21, s42, s37
	s_abs_i32 s37, s8
	s_xor_b32 s21, s21, s13
	s_sub_i32 s36, s21, s13
	s_mul_i32 s9, s36, s9
	s_sub_i32 s9, s10, s9
	s_add_i32 s42, s31, s9
	s_xor_b32 s8, s11, s8
	s_abs_i32 s9, s11
	s_sub_i32 s10, 0, s37
	s_ashr_i32 s8, s8, 31
	s_mov_b32 s11, 0xffffffff
	s_mul_i32 s10, s10, s11
	s_mul_hi_u32 s10, s11, s10
	s_add_i32 s11, s11, s10
	s_mul_hi_u32 s10, s9, s11
	s_mul_i32 s11, s10, s37
	s_sub_i32 s9, s9, s11
	s_add_i32 s11, s10, 1
	s_sub_i32 s13, s9, s37
	s_cmp_ge_u32 s9, s37
	s_cselect_b32 s10, s11, s10
	s_cselect_b32 s9, s13, s9
	s_add_i32 s11, s10, 1
	s_cmp_ge_u32 s9, s37
	s_cselect_b32 s9, s11, s10
	s_xor_b32 s9, s9, s8
	s_sub_i32 s48, s9, s8

;     __device__ __forceinline__ bool next(int i, Unit& u) const {
;         int nM = this->nM, nN = this->nN, Z2 = this->Z2; asm volatile("" : "+s"(nM), "+s"(nN), "+s"(Z2));
;         const long L = (long)i * G + c; if (L >= nwg) return false;
;         int wgid = (int)L; { const int q = nwg / NXCD, r = nwg % NXCD, xcd = wgid % NXCD, off = wgid / NXCD; wgid = (xcd < r ? xcd * (q + 1) : r * (q + 1) + (xcd - r) * q) + off; }
;         if (rev) wgid = nwg - 1 - wgid;
;         const int per = nM * nN, z = wgid / per, rem = wgid - z * per;
;         const int nig = WGM * nN, gid = rem / nig, fm = gid * WGM, gsz = (nM - fm) < WGM ? (nM - fm) : WGM, ri = rem - gid * nig;
;         u.pm = fm + (ri % gsz); u.pn = ri / gsz; u.z1 = z / Z2; u.z2 = z - u.z1 * Z2; return true;
; template <class Epi>
; __device__ __forceinline__ void gemm_phase(PG8_LAS unsigned char* lds, PG8_LAS unsigned char* xl, const Gemm g, const Sched& S, const Epi& E, const int wid) {
;     ...
;     if (!S.next(0, cur)) return;
.LBB0_1095:
	v_readlane_b32 s36, v253, 0
	v_readlane_b32 s37, v253, 1
	s_waitcnt lgkmcnt(0)
	s_barrier
	v_readlane_b32 s68, v252, 41
	s_load_dwordx4 s[48:51], s[36:37], 0xb0
	s_load_dwordx2 s[20:21], s[36:37], 0xd8
	v_readlane_b32 s4, v254, 40
	v_readlane_b32 s5, v254, 41
	s_mov_b32 s8, 1
	s_mov_b32 s1, 44
	v_cndmask_b32_e64 v0, 0, 1, s[4:5]
	s_movk_i32 s0, 0xa0
	v_cmp_ne_u32_e64 s[44:45], 1, v0
	s_andn2_b64 vcc, exec, s[4:5]
	v_mbcnt_lo_u32_b32 v12, -1, 0
	v_mbcnt_hi_u32_b32 v12, -1, v12
	s_cbranch_vccnz .LBB0_1097
	s_mul_i32 s8, s0, s1
	s_abs_i32 s8, s8
	s_sub_i32 s9, 0, s8
	v_readlane_b32 s4, v254, 55
	s_nop 0
	s_mov_b32 s10, 0x94f20
	s_mul_i32 s9, s9, s10
	s_mul_hi_u32 s9, s10, s9
	s_add_i32 s10, s10, s9
	s_mul_hi_u32 s9, s4, s10
	s_mul_i32 s9, s9, s8
	s_sub_i32 s9, s4, s9
	s_sub_i32 s10, s9, s8
	s_cmp_ge_u32 s9, s8
	s_cselect_b32 s9, s10, s9
	s_sub_i32 s10, s9, s8
	s_cmp_ge_u32 s9, s8
	s_cselect_b32 s8, s10, s9
	s_lshl_b32 s1, s1, 2
	s_abs_i32 s9, s1
	v_readlane_b32 s4, v254, 54
	s_sub_i32 s10, 0, s9
	s_xor_b32 s8, s8, s4
	s_sub_i32 s8, s8, s4
	s_abs_i32 s12, s8
	s_xor_b32 s11, s8, s1
	s_ashr_i32 s11, s11, 31
	s_mov_b32 s13, 0x1745d17
	s_mul_i32 s10, s10, s13
	s_mul_hi_u32 s10, s13, s10
	s_add_i32 s13, s13, s10
	s_mul_hi_u32 s10, s12, s13
	s_mul_i32 s13, s10, s9
	s_sub_i32 s12, s12, s13
	s_add_i32 s30, s10, 1
	s_sub_i32 s13, s12, s9
	s_cmp_ge_u32 s12, s9
	s_cselect_b32 s10, s30, s10
	s_cselect_b32 s12, s13, s12
	s_add_i32 s13, s10, 1
	s_cmp_ge_u32 s12, s9
	s_cselect_b32 s9, s13, s10
	s_xor_b32 s9, s9, s11
	s_sub_i32 s9, s9, s11
	s_lshl_b32 s10, s9, 2
	s_sub_i32 s0, s0, s10
	s_min_i32 s0, s0, 4
	s_abs_i32 s11, s0
	s_sub_i32 s12, 0, s11
	s_mul_i32 s9, s9, s1
	s_sub_i32 s1, s8, s9
	s_abs_i32 s8, s1
	s_xor_b32 s9, s1, s0
	s_ashr_i32 s9, s9, 31
	s_mov_b32 s13, 0x40000000
	s_mul_i32 s12, s12, s13
	s_mul_hi_u32 s12, s13, s12
	s_add_i32 s13, s13, s12
	s_mul_hi_u32 s12, s8, s13
	s_mul_i32 s13, s12, s11
	s_sub_i32 s8, s8, s13
	s_add_i32 s30, s12, 1
	s_sub_i32 s13, s8, s11
	s_cmp_ge_u32 s8, s11
	s_cselect_b32 s12, s30, s12
	s_cselect_b32 s8, s13, s8
	s_add_i32 s13, s12, 1
	s_cmp_ge_u32 s8, s11
	s_cselect_b32 s8, s13, s12
	s_xor_b32 s8, s8, s9
	s_sub_i32 s60, s8, s9
	s_mul_i32 s0, s60, s0
	s_sub_i32 s0, s1, s0
	s_add_i32 s12, s10, s0

;     __device__ __forceinline__ bool next(int i, Unit& u) const {
;         int nM = this->nM, nN = this->nN, Z2 = this->Z2; asm volatile("" : "+s"(nM), "+s"(nN), "+s"(Z2));
;         const long L = (long)i * G + c; if (L >= nwg) return false;
;         int wgid = (int)L; { const int q = nwg / NXCD, r = nwg % NXCD, xcd = wgid % NXCD, off = wgid / NXCD; wgid = (xcd < r ? xcd * (q + 1) : r * (q + 1) + (xcd - r) * q) + off; }
;         if (rev) wgid = nwg - 1 - wgid;
;         const int per = nM * nN, z = wgid / per, rem = wgid - z * per;
;         const int nig = WGM * nN, gid = rem / nig, fm = gid * WGM, gsz = (nM - fm) < WGM ? (nM - fm) : WGM, ri = rem - gid * nig;
;         u.pm = fm + (ri % gsz); u.pn = ri / gsz; u.z1 = z / Z2; u.z2 = z - u.z1 * Z2; return true;
; template <class Epi>
; __device__ __forceinline__ void gemm_phase(PG8_LAS unsigned char* lds, PG8_LAS unsigned char* xl, const Gemm g, const Sched& S, const Epi& E, const int wid) {
;     ...
;         const bool has_next = S.next(ui + 1, nxt);
.LBB0_1103:
	s_mov_b32 s10, 1
	s_mov_b32 s9, 44
	s_movk_i32 s8, 0xa0
	s_add_i32 s67, s67, 1
	s_mul_i32 s10, s67, s66
	s_mul_hi_u32 s11, s67, s68
	s_add_i32 s11, s11, s10
	s_mul_i32 s10, s67, s68
	s_add_u32 s10, s10, s2
	s_addc_u32 s11, s11, s33
	v_cmp_gt_i64_e32 vcc, s[10:11], v[208:209]
	v_cmp_lt_i64_e64 s[46:47], s[10:11], v[206:207]
	s_cbranch_vccnz .LBB0_1105
	s_ashr_i32 s11, s10, 31
	s_lshr_b32 s11, s11, 29
	s_add_i32 s11, s10, s11
	s_and_b32 s48, s11, -8
	s_sub_i32 s10, s10, s48
	s_ashr_i32 s11, s11, 3
	s_cmp_lt_i32 s10, 0
	s_movk_i32 s4, 0xfc8f
	s_mul_i32 s49, s8, s9
	s_cselect_b32 s48, s4, 0xfffffc90
	s_abs_i32 s49, s49
	s_mul_i32 s10, s10, s48
	s_sub_i32 s48, 0, s49
	s_sub_i32 s10, s10, s11
	s_addk_i32 s10, 0x1b7f
	s_ashr_i32 s11, s10, 31
	s_abs_i32 s10, s10
	s_mov_b32 s50, 0x94f20
	s_mul_i32 s48, s48, s50
	s_mul_hi_u32 s48, s50, s48
	s_add_i32 s50, s50, s48
	s_mul_hi_u32 s48, s10, s50
	s_mul_i32 s48, s48, s49
	s_sub_i32 s10, s10, s48
	s_sub_i32 s48, s10, s49
	s_cmp_ge_u32 s10, s49
	s_cselect_b32 s10, s48, s10
	s_sub_i32 s48, s10, s49
	s_cmp_ge_u32 s10, s49
	s_cselect_b32 s10, s48, s10
	s_lshl_b32 s9, s9, 2
	s_abs_i32 s48, s9
	s_xor_b32 s10, s10, s11
	s_sub_i32 s10, s10, s11
	s_sub_i32 s11, 0, s48
	s_abs_i32 s50, s10
	s_xor_b32 s49, s10, s9
	s_ashr_i32 s49, s49, 31
	s_mov_b32 s51, 0x1745d17
	s_mul_i32 s11, s11, s51
	s_mul_hi_u32 s11, s51, s11
	s_add_i32 s51, s51, s11
	s_mul_hi_u32 s11, s50, s51
	s_mul_i32 s51, s11, s48
	s_sub_i32 s50, s50, s51
	s_add_i32 s54, s11, 1
	s_sub_i32 s51, s50, s48
	s_cmp_ge_u32 s50, s48
	s_cselect_b32 s11, s54, s11
	s_cselect_b32 s50, s51, s50
	s_add_i32 s51, s11, 1
	s_cmp_ge_u32 s50, s48
	s_cselect_b32 s11, s51, s11
	s_xor_b32 s11, s11, s49
	s_sub_i32 s11, s11, s49
	s_lshl_b32 s49, s11, 2
	s_sub_i32 s8, s8, s49
	s_min_i32 s8, s8, 4
	s_abs_i32 s48, s8
	s_sub_i32 s50, 0, s48
	s_mul_i32 s11, s11, s9
	s_sub_i32 s9, s10, s11
	s_abs_i32 s10, s9
	s_xor_b32 s11, s9, s8
	s_ashr_i32 s11, s11, 31
	s_mov_b32 s51, 0x40000000
	s_mul_i32 s50, s50, s51
	s_mul_hi_u32 s50, s51, s50
	s_add_i32 s51, s51, s50
	s_mul_hi_u32 s50, s10, s51
	s_mul_i32 s51, s50, s48
	s_sub_i32 s10, s10, s51
	s_add_i32 s54, s50, 1
	s_sub_i32 s51, s10, s48
	s_cmp_ge_u32 s10, s48
	s_cselect_b32 s50, s54, s50
	s_cselect_b32 s10, s51, s10
	s_add_i32 s51, s50, 1
	s_cmp_ge_u32 s10, s48
	s_cselect_b32 s10, s51, s50
	s_xor_b32 s10, s10, s11
	s_sub_i32 s48, s10, s11
	s_mul_i32 s8, s48, s8
	s_sub_i32 s8, s9, s8
	s_add_i32 s50, s49, s8

;     __device__ __forceinline__ bool next(int i, Unit& u) const {
;         int nM = this->nM, nN = this->nN, Z2 = this->Z2; asm volatile("" : "+s"(nM), "+s"(nN), "+s"(Z2));
;         const long L = (long)i * G + c; if (L >= nwg) return false;
;         int wgid = (int)L; { const int q = nwg / NXCD, r = nwg % NXCD, xcd = wgid % NXCD, off = wgid / NXCD; wgid = (xcd < r ? xcd * (q + 1) : r * (q + 1) + (xcd - r) * q) + off; }
;         if (rev) wgid = nwg - 1 - wgid;
;         const int per = nM * nN, z = wgid / per, rem = wgid - z * per;
;         const int nig = WGM * nN, gid = rem / nig, fm = gid * WGM, gsz = (nM - fm) < WGM ? (nM - fm) : WGM, ri = rem - gid * nig;
;         u.pm = fm + (ri % gsz); u.pn = ri / gsz; u.z1 = z / Z2; u.z2 = z - u.z1 * Z2; return true;
; template <class Epi>
; __device__ __forceinline__ void gemm_phase(PG8_LAS unsigned char* lds, PG8_LAS unsigned char* xl, const Gemm g, const Sched& S, const Epi& E, const int wid) {
;     ...
;     if (!S.next(0, cur)) return;
.LBB0_1289:
	v_readlane_b32 s0, v253, 0
	v_readlane_b32 s1, v253, 1
	v_readlane_b32 s46, v252, 41
	s_waitcnt lgkmcnt(0)
	s_barrier
	s_load_dwordx2 s[20:21], s[0:1], 0xd8
	v_readlane_b32 s4, v252, 46
	s_mov_b32 s8, 8
	s_mov_b32 s0, 1
	s_movk_i32 s1, 0xa0
	v_readlane_b32 s5, v252, 47
	v_mbcnt_lo_u32_b32 v8, -1, 0
	v_mbcnt_hi_u32_b32 v8, -1, v8
	s_and_b64 vcc, exec, s[4:5]
	s_cbranch_vccnz .LBB0_1291
	s_mul_i32 s0, s1, s8
	s_abs_i32 s0, s0
	s_sub_i32 s4, 0, s0
	v_readlane_b32 s9, v254, 63
	s_nop 0
	s_mov_b32 s5, 0x333333
	s_mul_i32 s4, s4, s5
	s_mul_hi_u32 s4, s5, s4
	s_add_i32 s5, s5, s4
	s_mul_hi_u32 s4, s9, s5
	s_mul_i32 s4, s4, s0
	s_sub_i32 s4, s9, s4
	s_sub_i32 s5, s4, s0
	s_cmp_ge_u32 s4, s0
	s_cselect_b32 s4, s5, s4
	s_sub_i32 s5, s4, s0
	s_cmp_ge_u32 s4, s0
	s_cselect_b32 s0, s5, s4
	s_lshl_b32 s4, s8, 2
	s_abs_i32 s5, s4
	v_readlane_b32 s8, v254, 61
	s_xor_b32 s0, s0, s8
	s_sub_i32 s0, s0, s8
	s_sub_i32 s8, 0, s5
	s_abs_i32 s10, s0
	s_xor_b32 s9, s0, s4
	s_ashr_i32 s9, s9, 31
	s_mov_b32 s11, 0x8000000
	s_mul_i32 s8, s8, s11
	s_mul_hi_u32 s8, s11, s8
	s_add_i32 s11, s11, s8
	s_mul_hi_u32 s8, s10, s11
	s_mul_i32 s11, s8, s5
	s_sub_i32 s10, s10, s11
	s_add_i32 s12, s8, 1
	s_sub_i32 s11, s10, s5
	s_cmp_ge_u32 s10, s5
	s_cselect_b32 s8, s12, s8
	s_cselect_b32 s10, s11, s10
	s_add_i32 s11, s8, 1
	s_cmp_ge_u32 s10, s5
	s_cselect_b32 s5, s11, s8
	s_xor_b32 s5, s5, s9
	s_sub_i32 s5, s5, s9
	s_lshl_b32 s8, s5, 2
	s_sub_i32 s1, s1, s8
	s_min_i32 s1, s1, 4
	s_abs_i32 s9, s1
	s_sub_i32 s10, 0, s9
	s_mul_i32 s5, s5, s4
	s_sub_i32 s4, s0, s5
	s_abs_i32 s0, s4
	s_xor_b32 s5, s4, s1
	s_ashr_i32 s5, s5, 31
	s_mov_b32 s11, 0x40000000
	s_mul_i32 s10, s10, s11
	s_mul_hi_u32 s10, s11, s10
	s_add_i32 s11, s11, s10
	s_mul_hi_u32 s10, s0, s11
	s_mul_i32 s11, s10, s9
	s_sub_i32 s0, s0, s11
	s_add_i32 s12, s10, 1
	s_sub_i32 s11, s0, s9
	s_cmp_ge_u32 s0, s9
	s_cselect_b32 s10, s12, s10
	s_cselect_b32 s0, s11, s0
	s_add_i32 s11, s10, 1
	s_cmp_ge_u32 s0, s9
	s_cselect_b32 s0, s11, s10
	s_xor_b32 s0, s0, s5
	s_sub_i32 s0, s0, s5
	s_mul_i32 s1, s0, s1
	s_sub_i32 s1, s4, s1
	s_add_i32 s12, s8, s1

;     __device__ __forceinline__ bool next(int i, Unit& u) const {
;         int nM = this->nM, nN = this->nN, Z2 = this->Z2; asm volatile("" : "+s"(nM), "+s"(nN), "+s"(Z2));
;         const long L = (long)i * G + c; if (L >= nwg) return false;
;         int wgid = (int)L; { const int q = nwg / NXCD, r = nwg % NXCD, xcd = wgid % NXCD, off = wgid / NXCD; wgid = (xcd < r ? xcd * (q + 1) : r * (q + 1) + (xcd - r) * q) + off; }
;         if (rev) wgid = nwg - 1 - wgid;
;         const int per = nM * nN, z = wgid / per, rem = wgid - z * per;
;         const int nig = WGM * nN, gid = rem / nig, fm = gid * WGM, gsz = (nM - fm) < WGM ? (nM - fm) : WGM, ri = rem - gid * nig;
;         u.pm = fm + (ri % gsz); u.pn = ri / gsz; u.z1 = z / Z2; u.z2 = z - u.z1 * Z2; return true;
; template <class Epi>
; __device__ __forceinline__ void gemm_phase(PG8_LAS unsigned char* lds, PG8_LAS unsigned char* xl, const Gemm g, const Sched& S, const Epi& E, const int wid) {
;     ...
;         const bool has_next = S.next(ui + 1, nxt);
.LBB0_1297:
	s_mov_b32 s8, 8
	s_mov_b32 s4, 1
	s_movk_i32 s1, 0xa0
	s_add_i32 s67, s67, 1
	s_mul_i32 s4, s67, s66
	s_mul_hi_u32 s5, s67, s46
	s_add_i32 s5, s5, s4
	s_mul_i32 s4, s67, s46
	s_add_u32 s10, s4, s2
	s_addc_u32 s11, s5, s33
	v_cmp_gt_i64_e32 vcc, s[10:11], v[202:203]
	v_cmp_lt_i64_e64 s[44:45], s[10:11], v[200:201]
	s_cbranch_vccnz .LBB0_1299
	s_ashr_i32 s4, s10, 31
	s_lshr_b32 s4, s4, 29
	s_add_i32 s4, s10, s4
	s_ashr_i32 s5, s4, 3
	s_and_b32 s4, s4, -8
	s_sub_i32 s4, s10, s4
	s_cmp_lt_i32 s4, 0
	s_movk_i32 s9, 0xa1
	s_mul_i32 s10, s1, s8
	s_cselect_b32 s9, s9, 0xa0
	s_abs_i32 s10, s10
	s_mul_i32 s4, s4, s9
	s_sub_i32 s9, 0, s10
	s_add_i32 s4, s4, s5
	s_ashr_i32 s5, s4, 31
	s_abs_i32 s4, s4
	s_mov_b32 s11, 0x333333
	s_mul_i32 s9, s9, s11
	s_mul_hi_u32 s9, s11, s9
	s_add_i32 s11, s11, s9
	s_mul_hi_u32 s9, s4, s11
	s_mul_i32 s9, s9, s10
	s_sub_i32 s4, s4, s9
	s_sub_i32 s9, s4, s10
	s_cmp_ge_u32 s4, s10
	s_cselect_b32 s4, s9, s4
	s_sub_i32 s9, s4, s10
	s_cmp_ge_u32 s4, s10
	s_cselect_b32 s4, s9, s4
	s_lshl_b32 s8, s8, 2
	s_abs_i32 s9, s8
	s_xor_b32 s4, s4, s5
	s_sub_i32 s4, s4, s5
	s_sub_i32 s5, 0, s9
	s_abs_i32 s11, s4
	s_xor_b32 s10, s4, s8
	s_ashr_i32 s10, s10, 31
	s_mov_b32 s13, 0x8000000
	s_mul_i32 s5, s5, s13
	s_mul_hi_u32 s5, s13, s5
	s_add_i32 s13, s13, s5
	s_mul_hi_u32 s5, s11, s13
	s_mul_i32 s13, s5, s9
	s_sub_i32 s11, s11, s13
	s_add_i32 s20, s5, 1
	s_sub_i32 s13, s11, s9
	s_cmp_ge_u32 s11, s9
	s_cselect_b32 s5, s20, s5
	s_cselect_b32 s11, s13, s11
	s_add_i32 s13, s5, 1
	s_cmp_ge_u32 s11, s9
	s_cselect_b32 s5, s13, s5
	s_xor_b32 s5, s5, s10
	s_sub_i32 s5, s5, s10
	s_lshl_b32 s9, s5, 2
	s_sub_i32 s1, s1, s9
	s_min_i32 s1, s1, 4
	s_abs_i32 s10, s1
	s_sub_i32 s11, 0, s10
	s_mul_i32 s5, s5, s8
	s_sub_i32 s4, s4, s5
	s_abs_i32 s5, s4
	s_xor_b32 s8, s4, s1
	s_ashr_i32 s8, s8, 31
	s_mov_b32 s13, 0x40000000
	s_mul_i32 s11, s11, s13
	s_mul_hi_u32 s11, s13, s11
	s_add_i32 s13, s13, s11
	s_mul_hi_u32 s11, s5, s13
	s_mul_i32 s13, s11, s10
	s_sub_i32 s5, s5, s13
	s_add_i32 s20, s11, 1
	s_sub_i32 s13, s5, s10
	s_cmp_ge_u32 s5, s10
	s_cselect_b32 s11, s20, s11
	s_cselect_b32 s5, s13, s5
	s_add_i32 s13, s11, 1
	s_cmp_ge_u32 s5, s10
	s_cselect_b32 s5, s13, s11
	s_xor_b32 s5, s5, s8
	s_sub_i32 s68, s5, s8
	s_mul_i32 s1, s68, s1
	s_sub_i32 s1, s4, s1
	s_add_i32 s69, s9, s1
